# v13 + static s_setprio 1 for waves 0-3 during conv/DeltaNet/SSD/Hyena phases (older half leads its SIMD partner)
# baseline (speedup 1.0000x reference)
; #define LAS __attribute__((address_space(3)))
; __device__ __forceinline__ void ph_conv_inplace(lds_u8* lds, bf16_t* XT, const float* convw, const bf16_t* halo, int norm_mode) {
;     LAS bf16_t* raw = (LAS bf16_t*)lds;
;     const int tid = threadIdx.x, g8 = tid & 15;
;     vu4 pb0, pb1, ph = (vu4){0u, 0u, 0u, 0u};
;     ...
;     if ((int)blockIdx.x < 640 * 48) CONV_FETCH((int)blockIdx.x);
;     for (int u = blockIdx.x; u < 640 * 48; u += gridDim.x) {
.LBB0_348:
	v_readfirstlane_b32 s0, v0
	s_nop 0
	s_cmp_ge_u32 s0, 0x100
	s_cbranch_scc1 .Lprio_skip_0
	s_setprio 1

; #define PH(k, ...) if (IN(k)) { __VA_ARGS__ if (DUP(k)) { xcd_barrier(bar); __VA_ARGS__ } SEAM(k); }
; __global__ void __launch_bounds__(512, 2) mega_fwd(const Args args) {
;     ...
;     PH(3, ph_conv_inplace(lds, DNXT, ARG_IN(11), DNHALO, 1);)
;     PH(4, ph_dn_core2(args, lds, (const bf16_t*)(AR + 850 * MiB), DNXT, H, HO);
.LBB0_435:
	s_or_b64 exec, exec, s[0:1]
	s_waitcnt lgkmcnt(0)
	s_barrier
	s_setprio 0
